# v83 + write-through (sc0 sc1) on the bf16 weight-conversion stores (P0 and the two idle rounds)
# baseline (speedup 1.0000x reference)
.LBB0_76:
	v_mul_f32_e32 v137, v62, v156
	v_mul_f32_e32 v153, v66, v157
	v_cvt_pk_bf16_f32 v137, v137, v153
	ds_write_b32 v168, v137 offset:112
	v_mul_f32_e32 v137, v63, v156
	v_mul_f32_e32 v153, v67, v157
	v_cvt_pk_bf16_f32 v137, v137, v153
	ds_write_b32 v168, v137 offset:244
	v_mul_f32_e32 v137, v64, v156
	v_mul_f32_e32 v153, v68, v157
	v_cvt_pk_bf16_f32 v137, v137, v153
	ds_write_b32 v168, v137 offset:376
	v_mul_f32_e32 v137, v65, v156
	v_mul_f32_e32 v153, v69, v157
	v_cvt_pk_bf16_f32 v137, v137, v153
	ds_write_b32 v168, v137 offset:508
	ds_read2_b32 v[172:173], v169 offset1:1
	ds_read2_b32 v[174:175], v169 offset0:2 offset1:3
	v_mad_u64_u32 v[156:157], s[4:5], s19, v134, 0
	v_add_u32_e32 v153, 0x420, v169
	v_lshl_add_u64 v[156:157], v[156:157], 1, s[8:9]
	v_add_u32_e32 v171, 0x428, v169
	ds_read2_b32 v[176:177], v153 offset1:1
	ds_read2_b32 v[178:179], v171 offset1:1
	v_lshl_add_u64 v[156:157], v[156:157], 0, v[2:3]
	s_waitcnt lgkmcnt(2)
	global_store_dwordx4 v[156:157], v[172:175], off sc0 sc1
	v_mad_u64_u32 v[156:157], s[4:5], s19, v138, 0
	v_lshl_add_u64 v[156:157], v[156:157], 1, s[8:9]
	v_lshl_add_u64 v[156:157], v[156:157], 0, v[2:3]
	v_cmp_gt_i32_e32 vcc, s36, v140
	s_waitcnt lgkmcnt(0)
	global_store_dwordx4 v[156:157], v[176:179], off sc0 sc1
	s_and_saveexec_b64 s[4:5], vcc
	s_cbranch_execz .LBB0_83
	v_add_u32_e32 v137, 0x840, v169
	v_add_u32_e32 v155, 0x848, v169
	ds_read2_b32 v[172:173], v137 offset1:1
	ds_read2_b32 v[174:175], v155 offset1:1
	v_mad_u64_u32 v[156:157], s[20:21], s19, v140, 0
	v_lshl_add_u64 v[156:157], v[156:157], 1, s[8:9]
	v_lshl_add_u64 v[156:157], v[156:157], 0, v[2:3]
	s_waitcnt lgkmcnt(0)
	global_store_dwordx4 v[156:157], v[172:175], off sc0 sc1
	s_or_b64 exec, exec, s[4:5]
	v_cmp_gt_i32_e32 vcc, s36, v142
	s_and_saveexec_b64 s[4:5], vcc
	s_cbranch_execnz .LBB0_84

.LBB0_79:
	v_add_u32_e32 v137, 0x1080, v169
	v_add_u32_e32 v155, 0x1088, v169
	ds_read2_b32 v[172:173], v137 offset1:1
	ds_read2_b32 v[174:175], v155 offset1:1
	v_mad_u64_u32 v[156:157], s[20:21], s19, v144, 0
	v_lshl_add_u64 v[156:157], v[156:157], 1, s[8:9]
	v_lshl_add_u64 v[156:157], v[156:157], 0, v[2:3]
	s_waitcnt lgkmcnt(0)
	global_store_dwordx4 v[156:157], v[172:175], off sc0 sc1
	s_or_b64 exec, exec, s[4:5]
	v_cmp_gt_i32_e32 vcc, s36, v146
	s_and_saveexec_b64 s[4:5], vcc
	s_cbranch_execnz .LBB0_86

.LBB0_81:
	v_add_u32_e32 v137, 0x18c0, v169
	v_add_u32_e32 v155, 0x18c8, v169
	ds_read2_b32 v[172:173], v137 offset1:1
	ds_read2_b32 v[174:175], v155 offset1:1
	v_mad_u64_u32 v[156:157], s[20:21], s19, v148, 0
	v_lshl_add_u64 v[156:157], v[156:157], 1, s[8:9]
	v_lshl_add_u64 v[156:157], v[156:157], 0, v[2:3]
	s_waitcnt lgkmcnt(0)
	global_store_dwordx4 v[156:157], v[172:175], off sc0 sc1
	s_or_b64 exec, exec, s[4:5]
	v_cmp_gt_i32_e32 vcc, s36, v150
	s_and_saveexec_b64 s[4:5], vcc
	s_cbranch_execnz .LBB0_88

.LBB0_84:
	v_add_u32_e32 v137, 0xc60, v169
	v_add_u32_e32 v155, 0xc68, v169
	ds_read2_b32 v[172:173], v137 offset1:1
	ds_read2_b32 v[174:175], v155 offset1:1
	v_mad_u64_u32 v[156:157], s[20:21], s19, v142, 0
	v_lshl_add_u64 v[156:157], v[156:157], 1, s[8:9]
	v_lshl_add_u64 v[156:157], v[156:157], 0, v[2:3]
	s_waitcnt lgkmcnt(0)
	global_store_dwordx4 v[156:157], v[172:175], off sc0 sc1
	s_or_b64 exec, exec, s[4:5]
	v_cmp_gt_i32_e32 vcc, s36, v144
	s_and_saveexec_b64 s[4:5], vcc
	s_cbranch_execnz .LBB0_79

.LBB0_86:
	v_add_u32_e32 v137, 0x14a0, v169
	v_add_u32_e32 v155, 0x14a8, v169
	ds_read2_b32 v[172:173], v137 offset1:1
	ds_read2_b32 v[174:175], v155 offset1:1
	v_mad_u64_u32 v[156:157], s[20:21], s19, v146, 0
	v_lshl_add_u64 v[156:157], v[156:157], 1, s[8:9]
	v_lshl_add_u64 v[156:157], v[156:157], 0, v[2:3]
	s_waitcnt lgkmcnt(0)
	global_store_dwordx4 v[156:157], v[172:175], off sc0 sc1
	s_or_b64 exec, exec, s[4:5]
	v_cmp_gt_i32_e32 vcc, s36, v148
	s_and_saveexec_b64 s[4:5], vcc
	s_cbranch_execnz .LBB0_81

.LBB0_88:
	v_add_u32_e32 v137, 0x1ce0, v169
	v_add_u32_e32 v155, 0x1ce8, v169
	ds_read2_b32 v[172:173], v137 offset1:1
	ds_read2_b32 v[174:175], v155 offset1:1
	v_mad_u64_u32 v[156:157], s[20:21], s19, v150, 0
	v_lshl_add_u64 v[156:157], v[156:157], 1, s[8:9]
	v_lshl_add_u64 v[156:157], v[156:157], 0, v[2:3]
	s_waitcnt lgkmcnt(0)
	global_store_dwordx4 v[156:157], v[172:175], off sc0 sc1
	s_or_b64 exec, exec, s[4:5]
	s_andn2_b64 vcc, exec, s[14:15]
	s_mov_b64 s[14:15], 0
	s_cbranch_vccnz .LBB0_28

.LBB0_136:
	s_nop 0
	v_mul_f32_e32 v137, v126, v156
	v_mul_f32_e32 v155, v130, v157
	v_cvt_pk_bf16_f32 v137, v137, v155
	ds_write_b32 v168, v137 offset:112
	v_mul_f32_e32 v137, v127, v156
	v_mul_f32_e32 v155, v131, v157
	v_cvt_pk_bf16_f32 v137, v137, v155
	ds_write_b32 v168, v137 offset:244
	v_mul_f32_e32 v137, v128, v156
	v_mul_f32_e32 v155, v132, v157
	v_cvt_pk_bf16_f32 v137, v137, v155
	ds_write_b32 v168, v137 offset:376
	v_mul_f32_e32 v137, v129, v156
	v_mul_f32_e32 v155, v133, v157
	v_cvt_pk_bf16_f32 v137, v137, v155
	ds_write_b32 v168, v137 offset:508
	ds_read2_b32 v[172:173], v169 offset1:1
	ds_read2_b32 v[174:175], v169 offset0:2 offset1:3
	v_mad_u64_u32 v[156:157], s[4:5], s37, v134, 0
	v_lshl_add_u64 v[156:157], v[156:157], 1, s[12:13]
	ds_read2_b32 v[176:177], v153 offset1:1
	ds_read2_b32 v[178:179], v171 offset1:1
	v_lshl_add_u64 v[156:157], v[156:157], 0, v[2:3]
	s_waitcnt lgkmcnt(2)
	global_store_dwordx4 v[156:157], v[172:175], off sc0 sc1
	v_mad_u64_u32 v[156:157], s[4:5], s37, v138, 0
	v_lshl_add_u64 v[156:157], v[156:157], 1, s[12:13]
	v_lshl_add_u64 v[156:157], v[156:157], 0, v[2:3]
	v_cmp_gt_i32_e32 vcc, s39, v140
	s_waitcnt lgkmcnt(0)
	global_store_dwordx4 v[156:157], v[176:179], off sc0 sc1
	s_and_saveexec_b64 s[4:5], vcc
	s_cbranch_execz .LBB0_142
	v_add_u32_e32 v137, 0x840, v169
	v_add_u32_e32 v153, 0x848, v169
	ds_read2_b32 v[170:171], v137 offset1:1
	ds_read2_b32 v[172:173], v153 offset1:1
	v_mad_u64_u32 v[156:157], s[20:21], s37, v140, 0
	v_lshl_add_u64 v[156:157], v[156:157], 1, s[12:13]
	v_lshl_add_u64 v[156:157], v[156:157], 0, v[2:3]
	s_waitcnt lgkmcnt(0)
	global_store_dwordx4 v[156:157], v[170:173], off sc0 sc1
	s_or_b64 exec, exec, s[4:5]
	v_cmp_gt_i32_e32 vcc, s39, v142
	s_and_saveexec_b64 s[4:5], vcc
	s_cbranch_execnz .LBB0_143

.LBB0_139:
	v_add_u32_e32 v137, 0x1080, v169
	v_add_u32_e32 v153, 0x1088, v169
	ds_read2_b32 v[170:171], v137 offset1:1
	ds_read2_b32 v[172:173], v153 offset1:1
	v_mad_u64_u32 v[156:157], s[20:21], s37, v144, 0
	v_lshl_add_u64 v[156:157], v[156:157], 1, s[12:13]
	v_lshl_add_u64 v[156:157], v[156:157], 0, v[2:3]
	s_waitcnt lgkmcnt(0)
	global_store_dwordx4 v[156:157], v[170:173], off sc0 sc1
	s_or_b64 exec, exec, s[4:5]
	v_cmp_gt_i32_e32 vcc, s39, v146
	s_and_saveexec_b64 s[4:5], vcc
	s_cbranch_execnz .LBB0_145

.LBB0_141:
	v_add_u32_e32 v137, 0x18c0, v169
	v_add_u32_e32 v153, 0x18c8, v169
	ds_read2_b32 v[170:171], v137 offset1:1
	ds_read2_b32 v[172:173], v153 offset1:1
	v_mad_u64_u32 v[156:157], s[20:21], s37, v148, 0
	v_lshl_add_u64 v[156:157], v[156:157], 1, s[12:13]
	v_lshl_add_u64 v[156:157], v[156:157], 0, v[2:3]
	s_waitcnt lgkmcnt(0)
	global_store_dwordx4 v[156:157], v[170:173], off sc0 sc1
	s_or_b64 exec, exec, s[4:5]
	v_cmp_gt_i32_e32 vcc, s39, v150
	s_and_saveexec_b64 s[4:5], vcc
	s_cbranch_execz .LBB0_27
	s_branch .LBB0_147

.LBB0_143:
	v_add_u32_e32 v137, 0xc60, v169
	v_add_u32_e32 v153, 0xc68, v169
	ds_read2_b32 v[170:171], v137 offset1:1
	ds_read2_b32 v[172:173], v153 offset1:1
	v_mad_u64_u32 v[156:157], s[20:21], s37, v142, 0
	v_lshl_add_u64 v[156:157], v[156:157], 1, s[12:13]
	v_lshl_add_u64 v[156:157], v[156:157], 0, v[2:3]
	s_waitcnt lgkmcnt(0)
	global_store_dwordx4 v[156:157], v[170:173], off sc0 sc1
	s_or_b64 exec, exec, s[4:5]
	v_cmp_gt_i32_e32 vcc, s39, v144
	s_and_saveexec_b64 s[4:5], vcc
	s_cbranch_execnz .LBB0_139

.LBB0_145:
	v_add_u32_e32 v137, 0x14a0, v169
	v_add_u32_e32 v153, 0x14a8, v169
	ds_read2_b32 v[170:171], v137 offset1:1
	ds_read2_b32 v[172:173], v153 offset1:1
	v_mad_u64_u32 v[156:157], s[20:21], s37, v146, 0
	v_lshl_add_u64 v[156:157], v[156:157], 1, s[12:13]
	v_lshl_add_u64 v[156:157], v[156:157], 0, v[2:3]
	s_waitcnt lgkmcnt(0)
	global_store_dwordx4 v[156:157], v[170:173], off sc0 sc1
	s_or_b64 exec, exec, s[4:5]
	v_cmp_gt_i32_e32 vcc, s39, v148
	s_and_saveexec_b64 s[4:5], vcc
	s_cbranch_execnz .LBB0_141

.LBB0_147:
	v_add_u32_e32 v137, 0x1ce0, v169
	v_add_u32_e32 v153, 0x1ce8, v169
	ds_read2_b32 v[170:171], v137 offset1:1
	ds_read2_b32 v[172:173], v153 offset1:1
	v_mad_u64_u32 v[156:157], s[20:21], s37, v150, 0
	v_lshl_add_u64 v[156:157], v[156:157], 1, s[12:13]
	v_lshl_add_u64 v[156:157], v[156:157], 0, v[2:3]
	s_waitcnt lgkmcnt(0)
	global_store_dwordx4 v[156:157], v[170:173], off sc0 sc1
	s_branch .LBB0_27

.LBB0_768:
	s_waitcnt vmcnt(1)
	v_mul_f32_e32 v157, v32, v186
	s_waitcnt vmcnt(0)
	v_mul_f32_e32 v159, v60, v187
	v_cvt_pk_bf16_f32 v157, v157, v159
	ds_write_b32 v149, v157 offset:112
	v_mul_f32_e32 v157, v33, v186
	v_mul_f32_e32 v159, v61, v187
	v_cvt_pk_bf16_f32 v157, v157, v159
	ds_write_b32 v149, v157 offset:244
	v_mul_f32_e32 v157, v34, v186
	v_mul_f32_e32 v159, v62, v187
	v_cvt_pk_bf16_f32 v157, v157, v159
	ds_write_b32 v149, v157 offset:376
	v_mul_f32_e32 v157, v35, v186
	v_mul_f32_e32 v159, v63, v187
	v_cvt_pk_bf16_f32 v157, v157, v159
	ds_write_b32 v149, v157 offset:508
	ds_read2_b32 v[186:187], v151 offset1:1
	ds_read2_b32 v[188:189], v151 offset0:2 offset1:3
	v_mad_u64_u32 v[190:191], s[6:7], s37, v130, 0
	v_lshl_add_u64 v[190:191], v[190:191], 1, s[10:11]
	ds_read2_b32 v[194:195], v153 offset1:1
	ds_read2_b32 v[196:197], v153 offset0:2 offset1:3
	v_lshl_add_u64 v[190:191], v[190:191], 0, v[166:167]
	s_waitcnt lgkmcnt(2)
	global_store_dwordx4 v[190:191], v[186:189], off sc0 sc1
	v_cmp_gt_i32_e32 vcc, s38, v170
	s_nop 0
	v_mad_u64_u32 v[186:187], s[6:7], s37, v168, 0
	v_lshl_add_u64 v[186:187], v[186:187], 1, s[10:11]
	v_lshl_add_u64 v[186:187], v[186:187], 0, v[166:167]
	s_waitcnt lgkmcnt(0)
	global_store_dwordx4 v[186:187], v[194:197], off sc0 sc1
	s_and_saveexec_b64 s[6:7], vcc
	s_cbranch_execz .LBB0_775
	v_add_u32_e32 v157, v135, v137
	ds_read2_b32 v[186:187], v157 offset1:1
	ds_read2_b32 v[188:189], v157 offset0:2 offset1:3
	v_mad_u64_u32 v[190:191], s[20:21], s37, v170, 0
	v_lshl_add_u64 v[190:191], v[190:191], 1, s[10:11]
	v_lshl_add_u64 v[190:191], v[190:191], 0, v[166:167]
	s_waitcnt lgkmcnt(0)
	global_store_dwordx4 v[190:191], v[186:189], off sc0 sc1
	s_or_b64 exec, exec, s[6:7]
	v_cmp_gt_i32_e32 vcc, s38, v172
	s_and_saveexec_b64 s[6:7], vcc
	s_cbranch_execnz .LBB0_776

.LBB0_771:
	v_add_u32_e32 v157, v135, v141
	ds_read2_b32 v[186:187], v157 offset1:1
	ds_read2_b32 v[188:189], v157 offset0:2 offset1:3
	v_mad_u64_u32 v[190:191], s[20:21], s37, v174, 0
	v_lshl_add_u64 v[190:191], v[190:191], 1, s[10:11]
	v_lshl_add_u64 v[190:191], v[190:191], 0, v[166:167]
	s_waitcnt lgkmcnt(0)
	global_store_dwordx4 v[190:191], v[186:189], off sc0 sc1
	s_or_b64 exec, exec, s[6:7]
	v_cmp_gt_i32_e32 vcc, s38, v176
	s_and_saveexec_b64 s[6:7], vcc
	s_cbranch_execnz .LBB0_778

.LBB0_773:
	v_add_u32_e32 v157, v135, v145
	ds_read2_b32 v[186:187], v157 offset1:1
	ds_read2_b32 v[188:189], v157 offset0:2 offset1:3
	v_mad_u64_u32 v[190:191], s[20:21], s37, v178, 0
	v_lshl_add_u64 v[190:191], v[190:191], 1, s[10:11]
	v_lshl_add_u64 v[190:191], v[190:191], 0, v[166:167]
	s_waitcnt lgkmcnt(0)
	global_store_dwordx4 v[190:191], v[186:189], off sc0 sc1
	s_or_b64 exec, exec, s[6:7]
	v_cmp_gt_i32_e32 vcc, s38, v180
	s_and_saveexec_b64 s[6:7], vcc
	s_cbranch_execnz .LBB0_780

.LBB0_776:
	v_add_u32_e32 v157, v135, v139
	ds_read2_b32 v[186:187], v157 offset1:1
	ds_read2_b32 v[188:189], v157 offset0:2 offset1:3
	v_mad_u64_u32 v[190:191], s[20:21], s37, v172, 0
	v_lshl_add_u64 v[190:191], v[190:191], 1, s[10:11]
	v_lshl_add_u64 v[190:191], v[190:191], 0, v[166:167]
	s_waitcnt lgkmcnt(0)
	global_store_dwordx4 v[190:191], v[186:189], off sc0 sc1
	s_or_b64 exec, exec, s[6:7]
	v_cmp_gt_i32_e32 vcc, s38, v174
	s_and_saveexec_b64 s[6:7], vcc
	s_cbranch_execnz .LBB0_771

.LBB0_778:
	v_add_u32_e32 v157, v135, v143
	ds_read2_b32 v[186:187], v157 offset1:1
	ds_read2_b32 v[188:189], v157 offset0:2 offset1:3
	v_mad_u64_u32 v[190:191], s[20:21], s37, v176, 0
	v_lshl_add_u64 v[190:191], v[190:191], 1, s[10:11]
	v_lshl_add_u64 v[190:191], v[190:191], 0, v[166:167]
	s_waitcnt lgkmcnt(0)
	global_store_dwordx4 v[190:191], v[186:189], off sc0 sc1
	s_or_b64 exec, exec, s[6:7]
	v_cmp_gt_i32_e32 vcc, s38, v178
	s_and_saveexec_b64 s[6:7], vcc
	s_cbranch_execnz .LBB0_773

.LBB0_780:
	v_add_u32_e32 v157, v135, v147
	ds_read2_b32 v[186:187], v157 offset1:1
	ds_read2_b32 v[188:189], v157 offset0:2 offset1:3
	v_mad_u64_u32 v[190:191], s[20:21], s37, v180, 0
	v_lshl_add_u64 v[190:191], v[190:191], 1, s[10:11]
	v_lshl_add_u64 v[190:191], v[190:191], 0, v[166:167]
	s_waitcnt lgkmcnt(0)
	global_store_dwordx4 v[190:191], v[186:189], off sc0 sc1
	s_or_b64 exec, exec, s[6:7]
	s_andn2_b64 vcc, exec, s[18:19]
	s_mov_b64 s[18:19], 0
	s_cbranch_vccnz .LBB0_708

.LBB0_841:
	s_nop 0
	v_mul_f32_e32 v155, v120, v186
	v_mul_f32_e32 v157, v124, v187
	v_cvt_pk_bf16_f32 v155, v155, v157
	ds_write_b32 v149, v155 offset:112
	v_mul_f32_e32 v155, v121, v186
	v_mul_f32_e32 v157, v125, v187
	v_cvt_pk_bf16_f32 v155, v155, v157
	ds_write_b32 v149, v155 offset:244
	v_mul_f32_e32 v155, v122, v186
	v_mul_f32_e32 v157, v126, v187
	v_cvt_pk_bf16_f32 v155, v155, v157
	ds_write_b32 v149, v155 offset:376
	v_mul_f32_e32 v155, v123, v186
	v_mul_f32_e32 v157, v127, v187
	v_cvt_pk_bf16_f32 v155, v155, v157
	ds_write_b32 v149, v155 offset:508
	ds_read2_b32 v[186:187], v151 offset1:1
	ds_read2_b32 v[188:189], v151 offset0:2 offset1:3
	v_mad_u64_u32 v[190:191], s[6:7], s41, v130, 0
	v_lshl_add_u64 v[190:191], v[190:191], 1, s[16:17]
	ds_read2_b32 v[194:195], v153 offset1:1
	ds_read2_b32 v[196:197], v153 offset0:2 offset1:3
	v_lshl_add_u64 v[190:191], v[190:191], 0, v[166:167]
	s_waitcnt lgkmcnt(2)
	global_store_dwordx4 v[190:191], v[186:189], off sc0 sc1
	v_cmp_gt_i32_e32 vcc, s42, v170
	s_nop 0
	v_mad_u64_u32 v[186:187], s[6:7], s41, v168, 0
	v_lshl_add_u64 v[186:187], v[186:187], 1, s[16:17]
	v_lshl_add_u64 v[186:187], v[186:187], 0, v[166:167]
	s_waitcnt lgkmcnt(0)
	global_store_dwordx4 v[186:187], v[194:197], off sc0 sc1
	s_and_saveexec_b64 s[6:7], vcc
	s_cbranch_execz .LBB0_847
	v_add_u32_e32 v155, v135, v137
	ds_read2_b32 v[186:187], v155 offset1:1
	ds_read2_b32 v[188:189], v155 offset0:2 offset1:3
	v_mad_u64_u32 v[190:191], s[20:21], s41, v170, 0
	v_lshl_add_u64 v[190:191], v[190:191], 1, s[16:17]
	v_lshl_add_u64 v[190:191], v[190:191], 0, v[166:167]
	s_waitcnt lgkmcnt(0)
	global_store_dwordx4 v[190:191], v[186:189], off sc0 sc1
	s_or_b64 exec, exec, s[6:7]
	v_cmp_gt_i32_e32 vcc, s42, v172
	s_and_saveexec_b64 s[6:7], vcc
	s_cbranch_execnz .LBB0_848

.LBB0_844:
	v_add_u32_e32 v155, v135, v141
	ds_read2_b32 v[186:187], v155 offset1:1
	ds_read2_b32 v[188:189], v155 offset0:2 offset1:3
	v_mad_u64_u32 v[190:191], s[20:21], s41, v174, 0
	v_lshl_add_u64 v[190:191], v[190:191], 1, s[16:17]
	v_lshl_add_u64 v[190:191], v[190:191], 0, v[166:167]
	s_waitcnt lgkmcnt(0)
	global_store_dwordx4 v[190:191], v[186:189], off sc0 sc1
	s_or_b64 exec, exec, s[6:7]
	v_cmp_gt_i32_e32 vcc, s42, v176
	s_and_saveexec_b64 s[6:7], vcc
	s_cbranch_execnz .LBB0_850

.LBB0_846:
	v_add_u32_e32 v155, v135, v145
	ds_read2_b32 v[186:187], v155 offset1:1
	ds_read2_b32 v[188:189], v155 offset0:2 offset1:3
	v_mad_u64_u32 v[190:191], s[20:21], s41, v178, 0
	v_lshl_add_u64 v[190:191], v[190:191], 1, s[16:17]
	v_lshl_add_u64 v[190:191], v[190:191], 0, v[166:167]
	s_waitcnt lgkmcnt(0)
	global_store_dwordx4 v[190:191], v[186:189], off sc0 sc1
	s_or_b64 exec, exec, s[6:7]
	v_cmp_gt_i32_e32 vcc, s42, v180
	s_and_saveexec_b64 s[6:7], vcc
	s_cbranch_execz .LBB0_707
	s_branch .LBB0_852

.LBB0_848:
	v_add_u32_e32 v155, v135, v139
	ds_read2_b32 v[186:187], v155 offset1:1
	ds_read2_b32 v[188:189], v155 offset0:2 offset1:3
	v_mad_u64_u32 v[190:191], s[20:21], s41, v172, 0
	v_lshl_add_u64 v[190:191], v[190:191], 1, s[16:17]
	v_lshl_add_u64 v[190:191], v[190:191], 0, v[166:167]
	s_waitcnt lgkmcnt(0)
	global_store_dwordx4 v[190:191], v[186:189], off sc0 sc1
	s_or_b64 exec, exec, s[6:7]
	v_cmp_gt_i32_e32 vcc, s42, v174
	s_and_saveexec_b64 s[6:7], vcc
	s_cbranch_execnz .LBB0_844

.LBB0_850:
	v_add_u32_e32 v155, v135, v143
	ds_read2_b32 v[186:187], v155 offset1:1
	ds_read2_b32 v[188:189], v155 offset0:2 offset1:3
	v_mad_u64_u32 v[190:191], s[20:21], s41, v176, 0
	v_lshl_add_u64 v[190:191], v[190:191], 1, s[16:17]
	v_lshl_add_u64 v[190:191], v[190:191], 0, v[166:167]
	s_waitcnt lgkmcnt(0)
	global_store_dwordx4 v[190:191], v[186:189], off sc0 sc1
	s_or_b64 exec, exec, s[6:7]
	v_cmp_gt_i32_e32 vcc, s42, v178
	s_and_saveexec_b64 s[6:7], vcc
	s_cbranch_execnz .LBB0_846

.LBB0_852:
	v_add_u32_e32 v155, v135, v147
	ds_read2_b32 v[186:187], v155 offset1:1
	ds_read2_b32 v[188:189], v155 offset0:2 offset1:3
	v_mad_u64_u32 v[190:191], s[20:21], s41, v180, 0
	v_lshl_add_u64 v[190:191], v[190:191], 1, s[16:17]
	v_lshl_add_u64 v[190:191], v[190:191], 0, v[166:167]
	s_waitcnt lgkmcnt(0)
	global_store_dwordx4 v[190:191], v[186:189], off sc0 sc1
	s_branch .LBB0_707

.LBB0_1026:
	v_mul_f32_e32 v153, v32, v186
	v_mul_f32_e32 v155, v60, v187
	v_cvt_pk_bf16_f32 v153, v153, v155
	ds_write_b32 v145, v153 offset:112
	v_mul_f32_e32 v153, v33, v186
	v_mul_f32_e32 v155, v61, v187
	v_cvt_pk_bf16_f32 v153, v153, v155
	ds_write_b32 v145, v153 offset:244
	v_mul_f32_e32 v153, v34, v186
	v_mul_f32_e32 v155, v62, v187
	v_cvt_pk_bf16_f32 v153, v153, v155
	ds_write_b32 v145, v153 offset:376
	v_mul_f32_e32 v153, v35, v186
	v_mul_f32_e32 v155, v63, v187
	v_cvt_pk_bf16_f32 v153, v153, v155
	ds_write_b32 v145, v153 offset:508
	ds_read2_b32 v[186:187], v147 offset1:1
	ds_read2_b32 v[188:189], v147 offset0:2 offset1:3
	v_mad_u64_u32 v[190:191], s[6:7], s37, v130, 0
	v_lshl_add_u64 v[190:191], v[190:191], 1, s[10:11]
	ds_read2_b32 v[194:195], v149 offset1:1
	ds_read2_b32 v[196:197], v149 offset0:2 offset1:3
	v_lshl_add_u64 v[190:191], v[190:191], 0, v[166:167]
	s_waitcnt lgkmcnt(2)
	global_store_dwordx4 v[190:191], v[186:189], off sc0 sc1
	v_cmp_gt_i32_e32 vcc, s39, v170
	s_nop 0
	v_mad_u64_u32 v[186:187], s[6:7], s37, v168, 0
	v_lshl_add_u64 v[186:187], v[186:187], 1, s[10:11]
	v_lshl_add_u64 v[186:187], v[186:187], 0, v[166:167]
	s_waitcnt lgkmcnt(0)
	global_store_dwordx4 v[186:187], v[194:197], off sc0 sc1
	s_and_saveexec_b64 s[6:7], vcc
	s_cbranch_execz .LBB0_1033
	v_add_u32_e32 v153, v129, v131
	ds_read2_b32 v[186:187], v153 offset1:1
	ds_read2_b32 v[188:189], v153 offset0:2 offset1:3
	v_mad_u64_u32 v[190:191], s[20:21], s37, v170, 0
	v_lshl_add_u64 v[190:191], v[190:191], 1, s[10:11]
	v_lshl_add_u64 v[190:191], v[190:191], 0, v[166:167]
	s_waitcnt lgkmcnt(0)
	global_store_dwordx4 v[190:191], v[186:189], off sc0 sc1
	s_or_b64 exec, exec, s[6:7]
	v_cmp_gt_i32_e32 vcc, s39, v172
	s_and_saveexec_b64 s[6:7], vcc
	s_cbranch_execnz .LBB0_1034

.LBB0_1029:
	v_add_u32_e32 v153, v129, v137
	ds_read2_b32 v[186:187], v153 offset1:1
	ds_read2_b32 v[188:189], v153 offset0:2 offset1:3
	v_mad_u64_u32 v[190:191], s[20:21], s37, v174, 0
	v_lshl_add_u64 v[190:191], v[190:191], 1, s[10:11]
	v_lshl_add_u64 v[190:191], v[190:191], 0, v[166:167]
	s_waitcnt lgkmcnt(0)
	global_store_dwordx4 v[190:191], v[186:189], off sc0 sc1
	s_or_b64 exec, exec, s[6:7]
	v_cmp_gt_i32_e32 vcc, s39, v176
	s_and_saveexec_b64 s[6:7], vcc
	s_cbranch_execnz .LBB0_1036

.LBB0_1031:
	v_add_u32_e32 v153, v129, v141
	ds_read2_b32 v[186:187], v153 offset1:1
	ds_read2_b32 v[188:189], v153 offset0:2 offset1:3
	v_mad_u64_u32 v[190:191], s[20:21], s37, v178, 0
	v_lshl_add_u64 v[190:191], v[190:191], 1, s[10:11]
	v_lshl_add_u64 v[190:191], v[190:191], 0, v[166:167]
	s_waitcnt lgkmcnt(0)
	global_store_dwordx4 v[190:191], v[186:189], off sc0 sc1
	s_or_b64 exec, exec, s[6:7]
	v_cmp_gt_i32_e32 vcc, s39, v180
	s_and_saveexec_b64 s[6:7], vcc
	s_cbranch_execnz .LBB0_1038

.LBB0_1034:
	v_add_u32_e32 v153, v129, v135
	ds_read2_b32 v[186:187], v153 offset1:1
	ds_read2_b32 v[188:189], v153 offset0:2 offset1:3
	v_mad_u64_u32 v[190:191], s[20:21], s37, v172, 0
	v_lshl_add_u64 v[190:191], v[190:191], 1, s[10:11]
	v_lshl_add_u64 v[190:191], v[190:191], 0, v[166:167]
	s_waitcnt lgkmcnt(0)
	global_store_dwordx4 v[190:191], v[186:189], off sc0 sc1
	s_or_b64 exec, exec, s[6:7]
	v_cmp_gt_i32_e32 vcc, s39, v174
	s_and_saveexec_b64 s[6:7], vcc
	s_cbranch_execnz .LBB0_1029

.LBB0_1036:
	v_add_u32_e32 v153, v129, v139
	ds_read2_b32 v[186:187], v153 offset1:1
	ds_read2_b32 v[188:189], v153 offset0:2 offset1:3
	v_mad_u64_u32 v[190:191], s[20:21], s37, v176, 0
	v_lshl_add_u64 v[190:191], v[190:191], 1, s[10:11]
	v_lshl_add_u64 v[190:191], v[190:191], 0, v[166:167]
	s_waitcnt lgkmcnt(0)
	global_store_dwordx4 v[190:191], v[186:189], off sc0 sc1
	s_or_b64 exec, exec, s[6:7]
	v_cmp_gt_i32_e32 vcc, s39, v178
	s_and_saveexec_b64 s[6:7], vcc
	s_cbranch_execnz .LBB0_1031

.LBB0_1038:
	v_add_u32_e32 v153, v129, v143
	ds_read2_b32 v[186:187], v153 offset1:1
	ds_read2_b32 v[188:189], v153 offset0:2 offset1:3
	v_mad_u64_u32 v[190:191], s[20:21], s37, v180, 0
	v_lshl_add_u64 v[190:191], v[190:191], 1, s[10:11]
	v_lshl_add_u64 v[190:191], v[190:191], 0, v[166:167]
	s_waitcnt lgkmcnt(0)
	global_store_dwordx4 v[190:191], v[186:189], off sc0 sc1
	s_or_b64 exec, exec, s[6:7]
	s_andn2_b64 vcc, exec, s[18:19]
	s_mov_b64 s[18:19], 0
	s_cbranch_vccnz .LBB0_966

.LBB0_1099:
	s_nop 0
	v_mul_f32_e32 v151, v120, v186
	v_mul_f32_e32 v153, v124, v187
	v_cvt_pk_bf16_f32 v151, v151, v153
	ds_write_b32 v145, v151 offset:112
	v_mul_f32_e32 v151, v121, v186
	v_mul_f32_e32 v153, v125, v187
	v_cvt_pk_bf16_f32 v151, v151, v153
	ds_write_b32 v145, v151 offset:244
	v_mul_f32_e32 v151, v122, v186
	v_mul_f32_e32 v153, v126, v187
	v_cvt_pk_bf16_f32 v151, v151, v153
	ds_write_b32 v145, v151 offset:376
	v_mul_f32_e32 v151, v123, v186
	v_mul_f32_e32 v153, v127, v187
	v_cvt_pk_bf16_f32 v151, v151, v153
	ds_write_b32 v145, v151 offset:508
	ds_read2_b32 v[186:187], v147 offset1:1
	ds_read2_b32 v[188:189], v147 offset0:2 offset1:3
	v_mad_u64_u32 v[190:191], s[6:7], s40, v130, 0
	v_lshl_add_u64 v[190:191], v[190:191], 1, s[16:17]
	ds_read2_b32 v[194:195], v149 offset1:1
	ds_read2_b32 v[196:197], v149 offset0:2 offset1:3
	v_lshl_add_u64 v[190:191], v[190:191], 0, v[166:167]
	s_waitcnt lgkmcnt(2)
	global_store_dwordx4 v[190:191], v[186:189], off sc0 sc1
	v_cmp_gt_i32_e32 vcc, s41, v170
	s_nop 0
	v_mad_u64_u32 v[186:187], s[6:7], s40, v168, 0
	v_lshl_add_u64 v[186:187], v[186:187], 1, s[16:17]
	v_lshl_add_u64 v[186:187], v[186:187], 0, v[166:167]
	s_waitcnt lgkmcnt(0)
	global_store_dwordx4 v[186:187], v[194:197], off sc0 sc1
	s_and_saveexec_b64 s[6:7], vcc
	s_cbranch_execz .LBB0_1105
	v_add_u32_e32 v151, v129, v131
	ds_read2_b32 v[186:187], v151 offset1:1
	ds_read2_b32 v[188:189], v151 offset0:2 offset1:3
	v_mad_u64_u32 v[190:191], s[20:21], s40, v170, 0
	v_lshl_add_u64 v[190:191], v[190:191], 1, s[16:17]
	v_lshl_add_u64 v[190:191], v[190:191], 0, v[166:167]
	s_waitcnt lgkmcnt(0)
	global_store_dwordx4 v[190:191], v[186:189], off sc0 sc1
	s_or_b64 exec, exec, s[6:7]
	v_cmp_gt_i32_e32 vcc, s41, v172
	s_and_saveexec_b64 s[6:7], vcc
	s_cbranch_execnz .LBB0_1106

.LBB0_1102:
	v_add_u32_e32 v151, v129, v137
	ds_read2_b32 v[186:187], v151 offset1:1
	ds_read2_b32 v[188:189], v151 offset0:2 offset1:3
	v_mad_u64_u32 v[190:191], s[20:21], s40, v174, 0
	v_lshl_add_u64 v[190:191], v[190:191], 1, s[16:17]
	v_lshl_add_u64 v[190:191], v[190:191], 0, v[166:167]
	s_waitcnt lgkmcnt(0)
	global_store_dwordx4 v[190:191], v[186:189], off sc0 sc1
	s_or_b64 exec, exec, s[6:7]
	v_cmp_gt_i32_e32 vcc, s41, v176
	s_and_saveexec_b64 s[6:7], vcc
	s_cbranch_execnz .LBB0_1108

.LBB0_1104:
	v_add_u32_e32 v151, v129, v141
	ds_read2_b32 v[186:187], v151 offset1:1
	ds_read2_b32 v[188:189], v151 offset0:2 offset1:3
	v_mad_u64_u32 v[190:191], s[20:21], s40, v178, 0
	v_lshl_add_u64 v[190:191], v[190:191], 1, s[16:17]
	v_lshl_add_u64 v[190:191], v[190:191], 0, v[166:167]
	s_waitcnt lgkmcnt(0)
	global_store_dwordx4 v[190:191], v[186:189], off sc0 sc1
	s_or_b64 exec, exec, s[6:7]
	v_cmp_gt_i32_e32 vcc, s41, v180
	s_and_saveexec_b64 s[6:7], vcc
	s_cbranch_execz .LBB0_965
	s_branch .LBB0_1110

.LBB0_1106:
	v_add_u32_e32 v151, v129, v135
	ds_read2_b32 v[186:187], v151 offset1:1
	ds_read2_b32 v[188:189], v151 offset0:2 offset1:3
	v_mad_u64_u32 v[190:191], s[20:21], s40, v172, 0
	v_lshl_add_u64 v[190:191], v[190:191], 1, s[16:17]
	v_lshl_add_u64 v[190:191], v[190:191], 0, v[166:167]
	s_waitcnt lgkmcnt(0)
	global_store_dwordx4 v[190:191], v[186:189], off sc0 sc1
	s_or_b64 exec, exec, s[6:7]
	v_cmp_gt_i32_e32 vcc, s41, v174
	s_and_saveexec_b64 s[6:7], vcc
	s_cbranch_execnz .LBB0_1102

.LBB0_1108:
	v_add_u32_e32 v151, v129, v139
	ds_read2_b32 v[186:187], v151 offset1:1
	ds_read2_b32 v[188:189], v151 offset0:2 offset1:3
	v_mad_u64_u32 v[190:191], s[20:21], s40, v176, 0
	v_lshl_add_u64 v[190:191], v[190:191], 1, s[16:17]
	v_lshl_add_u64 v[190:191], v[190:191], 0, v[166:167]
	s_waitcnt lgkmcnt(0)
	global_store_dwordx4 v[190:191], v[186:189], off sc0 sc1
	s_or_b64 exec, exec, s[6:7]
	v_cmp_gt_i32_e32 vcc, s41, v178
	s_and_saveexec_b64 s[6:7], vcc
	s_cbranch_execnz .LBB0_1104

.LBB0_1110:
	v_add_u32_e32 v151, v129, v143
	ds_read2_b32 v[186:187], v151 offset1:1
	ds_read2_b32 v[188:189], v151 offset0:2 offset1:3
	v_mad_u64_u32 v[190:191], s[20:21], s40, v180, 0
	v_lshl_add_u64 v[190:191], v[190:191], 1, s[16:17]
	v_lshl_add_u64 v[190:191], v[190:191], 0, v[166:167]
	s_waitcnt lgkmcnt(0)
	global_store_dwordx4 v[190:191], v[186:189], off sc0 sc1
	s_branch .LBB0_965

.LBB0_1603:
	s_waitcnt vmcnt(1)
	v_mul_f32_e32 v157, v32, v186
	s_waitcnt vmcnt(0)
	v_mul_f32_e32 v159, v60, v187
	v_cvt_pk_bf16_f32 v157, v157, v159
	ds_write_b32 v149, v157 offset:112
	v_mul_f32_e32 v157, v33, v186
	v_mul_f32_e32 v159, v61, v187
	v_cvt_pk_bf16_f32 v157, v157, v159
	ds_write_b32 v149, v157 offset:244
	v_mul_f32_e32 v157, v34, v186
	v_mul_f32_e32 v159, v62, v187
	v_cvt_pk_bf16_f32 v157, v157, v159
	ds_write_b32 v149, v157 offset:376
	v_mul_f32_e32 v157, v35, v186
	v_mul_f32_e32 v159, v63, v187
	v_cvt_pk_bf16_f32 v157, v157, v159
	ds_write_b32 v149, v157 offset:508
	ds_read2_b32 v[186:187], v151 offset1:1
	ds_read2_b32 v[188:189], v151 offset0:2 offset1:3
	v_mad_u64_u32 v[190:191], s[6:7], s35, v130, 0
	v_lshl_add_u64 v[190:191], v[190:191], 1, s[10:11]
	ds_read2_b32 v[194:195], v153 offset1:1
	ds_read2_b32 v[196:197], v153 offset0:2 offset1:3
	v_lshl_add_u64 v[190:191], v[190:191], 0, v[166:167]
	s_waitcnt lgkmcnt(2)
	global_store_dwordx4 v[190:191], v[186:189], off sc0 sc1
	v_cmp_gt_i32_e32 vcc, s36, v170
	s_nop 0
	v_mad_u64_u32 v[186:187], s[6:7], s35, v168, 0
	v_lshl_add_u64 v[186:187], v[186:187], 1, s[10:11]
	v_lshl_add_u64 v[186:187], v[186:187], 0, v[166:167]
	s_waitcnt lgkmcnt(0)
	global_store_dwordx4 v[186:187], v[194:197], off sc0 sc1
	s_and_saveexec_b64 s[6:7], vcc
	s_cbranch_execz .LBB0_1610
	v_add_u32_e32 v157, v135, v137
	ds_read2_b32 v[186:187], v157 offset1:1
	ds_read2_b32 v[188:189], v157 offset0:2 offset1:3
	v_mad_u64_u32 v[190:191], s[18:19], s35, v170, 0
	v_lshl_add_u64 v[190:191], v[190:191], 1, s[10:11]
	v_lshl_add_u64 v[190:191], v[190:191], 0, v[166:167]
	s_waitcnt lgkmcnt(0)
	global_store_dwordx4 v[190:191], v[186:189], off sc0 sc1
	s_or_b64 exec, exec, s[6:7]
	v_cmp_gt_i32_e32 vcc, s36, v172
	s_and_saveexec_b64 s[6:7], vcc
	s_cbranch_execnz .LBB0_1611

.LBB0_1606:
	v_add_u32_e32 v157, v135, v141
	ds_read2_b32 v[186:187], v157 offset1:1
	ds_read2_b32 v[188:189], v157 offset0:2 offset1:3
	v_mad_u64_u32 v[190:191], s[18:19], s35, v174, 0
	v_lshl_add_u64 v[190:191], v[190:191], 1, s[10:11]
	v_lshl_add_u64 v[190:191], v[190:191], 0, v[166:167]
	s_waitcnt lgkmcnt(0)
	global_store_dwordx4 v[190:191], v[186:189], off sc0 sc1
	s_or_b64 exec, exec, s[6:7]
	v_cmp_gt_i32_e32 vcc, s36, v176
	s_and_saveexec_b64 s[6:7], vcc
	s_cbranch_execnz .LBB0_1613

.LBB0_1608:
	v_add_u32_e32 v157, v135, v145
	ds_read2_b32 v[186:187], v157 offset1:1
	ds_read2_b32 v[188:189], v157 offset0:2 offset1:3
	v_mad_u64_u32 v[190:191], s[18:19], s35, v178, 0
	v_lshl_add_u64 v[190:191], v[190:191], 1, s[10:11]
	v_lshl_add_u64 v[190:191], v[190:191], 0, v[166:167]
	s_waitcnt lgkmcnt(0)
	global_store_dwordx4 v[190:191], v[186:189], off sc0 sc1
	s_or_b64 exec, exec, s[6:7]
	v_cmp_gt_i32_e32 vcc, s36, v180
	s_and_saveexec_b64 s[6:7], vcc
	s_cbranch_execnz .LBB0_1615

.LBB0_1611:
	v_add_u32_e32 v157, v135, v139
	ds_read2_b32 v[186:187], v157 offset1:1
	ds_read2_b32 v[188:189], v157 offset0:2 offset1:3
	v_mad_u64_u32 v[190:191], s[18:19], s35, v172, 0
	v_lshl_add_u64 v[190:191], v[190:191], 1, s[10:11]
	v_lshl_add_u64 v[190:191], v[190:191], 0, v[166:167]
	s_waitcnt lgkmcnt(0)
	global_store_dwordx4 v[190:191], v[186:189], off sc0 sc1
	s_or_b64 exec, exec, s[6:7]
	v_cmp_gt_i32_e32 vcc, s36, v174
	s_and_saveexec_b64 s[6:7], vcc
	s_cbranch_execnz .LBB0_1606

.LBB0_1613:
	v_add_u32_e32 v157, v135, v143
	ds_read2_b32 v[186:187], v157 offset1:1
	ds_read2_b32 v[188:189], v157 offset0:2 offset1:3
	v_mad_u64_u32 v[190:191], s[18:19], s35, v176, 0
	v_lshl_add_u64 v[190:191], v[190:191], 1, s[10:11]
	v_lshl_add_u64 v[190:191], v[190:191], 0, v[166:167]
	s_waitcnt lgkmcnt(0)
	global_store_dwordx4 v[190:191], v[186:189], off sc0 sc1
	s_or_b64 exec, exec, s[6:7]
	v_cmp_gt_i32_e32 vcc, s36, v178
	s_and_saveexec_b64 s[6:7], vcc
	s_cbranch_execnz .LBB0_1608

.LBB0_1615:
	v_add_u32_e32 v157, v135, v147
	ds_read2_b32 v[186:187], v157 offset1:1
	ds_read2_b32 v[188:189], v157 offset0:2 offset1:3
	v_mad_u64_u32 v[190:191], s[18:19], s35, v180, 0
	v_lshl_add_u64 v[190:191], v[190:191], 1, s[10:11]
	v_lshl_add_u64 v[190:191], v[190:191], 0, v[166:167]
	s_waitcnt lgkmcnt(0)
	global_store_dwordx4 v[190:191], v[186:189], off sc0 sc1
	s_or_b64 exec, exec, s[6:7]
	s_andn2_b64 vcc, exec, s[16:17]
	s_mov_b64 s[16:17], 0
	s_cbranch_vccnz .LBB0_1540

.LBB0_1679:
	s_nop 0
	v_mul_f32_e32 v155, v120, v186
	v_mul_f32_e32 v157, v124, v187
	v_cvt_pk_bf16_f32 v155, v155, v157
	ds_write_b32 v149, v155 offset:112
	v_mul_f32_e32 v155, v121, v186
	v_mul_f32_e32 v157, v125, v187
	v_cvt_pk_bf16_f32 v155, v155, v157
	ds_write_b32 v149, v155 offset:244
	v_mul_f32_e32 v155, v122, v186
	v_mul_f32_e32 v157, v126, v187
	v_cvt_pk_bf16_f32 v155, v155, v157
	ds_write_b32 v149, v155 offset:376
	v_mul_f32_e32 v155, v123, v186
	v_mul_f32_e32 v157, v127, v187
	v_cvt_pk_bf16_f32 v155, v155, v157
	ds_write_b32 v149, v155 offset:508
	ds_read2_b32 v[186:187], v151 offset1:1
	ds_read2_b32 v[188:189], v151 offset0:2 offset1:3
	v_mad_u64_u32 v[190:191], s[6:7], s38, v130, 0
	v_lshl_add_u64 v[190:191], v[190:191], 1, s[14:15]
	ds_read2_b32 v[194:195], v153 offset1:1
	ds_read2_b32 v[196:197], v153 offset0:2 offset1:3
	v_lshl_add_u64 v[190:191], v[190:191], 0, v[166:167]
	s_waitcnt lgkmcnt(2)
	global_store_dwordx4 v[190:191], v[186:189], off sc0 sc1
	v_cmp_gt_i32_e32 vcc, s40, v170
	s_nop 0
	v_mad_u64_u32 v[186:187], s[6:7], s38, v168, 0
	v_lshl_add_u64 v[186:187], v[186:187], 1, s[14:15]
	v_lshl_add_u64 v[186:187], v[186:187], 0, v[166:167]
	s_waitcnt lgkmcnt(0)
	global_store_dwordx4 v[186:187], v[194:197], off sc0 sc1
	s_and_saveexec_b64 s[6:7], vcc
	s_cbranch_execz .LBB0_1685
	v_add_u32_e32 v155, v135, v137
	ds_read2_b32 v[186:187], v155 offset1:1
	ds_read2_b32 v[188:189], v155 offset0:2 offset1:3
	v_mad_u64_u32 v[190:191], s[18:19], s38, v170, 0
	v_lshl_add_u64 v[190:191], v[190:191], 1, s[14:15]
	v_lshl_add_u64 v[190:191], v[190:191], 0, v[166:167]
	s_waitcnt lgkmcnt(0)
	global_store_dwordx4 v[190:191], v[186:189], off sc0 sc1
	s_or_b64 exec, exec, s[6:7]
	v_cmp_gt_i32_e32 vcc, s40, v172
	s_and_saveexec_b64 s[6:7], vcc
	s_cbranch_execnz .LBB0_1686

.LBB0_1682:
	v_add_u32_e32 v155, v135, v141
	ds_read2_b32 v[186:187], v155 offset1:1
	ds_read2_b32 v[188:189], v155 offset0:2 offset1:3
	v_mad_u64_u32 v[190:191], s[18:19], s38, v174, 0
	v_lshl_add_u64 v[190:191], v[190:191], 1, s[14:15]
	v_lshl_add_u64 v[190:191], v[190:191], 0, v[166:167]
	s_waitcnt lgkmcnt(0)
	global_store_dwordx4 v[190:191], v[186:189], off sc0 sc1
	s_or_b64 exec, exec, s[6:7]
	v_cmp_gt_i32_e32 vcc, s40, v176
	s_and_saveexec_b64 s[6:7], vcc
	s_cbranch_execnz .LBB0_1688

.LBB0_1684:
	v_add_u32_e32 v155, v135, v145
	ds_read2_b32 v[186:187], v155 offset1:1
	ds_read2_b32 v[188:189], v155 offset0:2 offset1:3
	v_mad_u64_u32 v[190:191], s[18:19], s38, v178, 0
	v_lshl_add_u64 v[190:191], v[190:191], 1, s[14:15]
	v_lshl_add_u64 v[190:191], v[190:191], 0, v[166:167]
	s_waitcnt lgkmcnt(0)
	global_store_dwordx4 v[190:191], v[186:189], off sc0 sc1
	s_or_b64 exec, exec, s[6:7]
	v_cmp_gt_i32_e32 vcc, s40, v180
	s_and_saveexec_b64 s[6:7], vcc
	s_cbranch_execz .LBB0_1539
	s_branch .LBB0_1690

.LBB0_1686:
	v_add_u32_e32 v155, v135, v139
	ds_read2_b32 v[186:187], v155 offset1:1
	ds_read2_b32 v[188:189], v155 offset0:2 offset1:3
	v_mad_u64_u32 v[190:191], s[18:19], s38, v172, 0
	v_lshl_add_u64 v[190:191], v[190:191], 1, s[14:15]
	v_lshl_add_u64 v[190:191], v[190:191], 0, v[166:167]
	s_waitcnt lgkmcnt(0)
	global_store_dwordx4 v[190:191], v[186:189], off sc0 sc1
	s_or_b64 exec, exec, s[6:7]
	v_cmp_gt_i32_e32 vcc, s40, v174
	s_and_saveexec_b64 s[6:7], vcc
	s_cbranch_execnz .LBB0_1682

.LBB0_1688:
	v_add_u32_e32 v155, v135, v143
	ds_read2_b32 v[186:187], v155 offset1:1
	ds_read2_b32 v[188:189], v155 offset0:2 offset1:3
	v_mad_u64_u32 v[190:191], s[18:19], s38, v176, 0
	v_lshl_add_u64 v[190:191], v[190:191], 1, s[14:15]
	v_lshl_add_u64 v[190:191], v[190:191], 0, v[166:167]
	s_waitcnt lgkmcnt(0)
	global_store_dwordx4 v[190:191], v[186:189], off sc0 sc1
	s_or_b64 exec, exec, s[6:7]
	v_cmp_gt_i32_e32 vcc, s40, v178
	s_and_saveexec_b64 s[6:7], vcc
	s_cbranch_execnz .LBB0_1684

.LBB0_1690:
	v_add_u32_e32 v155, v135, v147
	ds_read2_b32 v[186:187], v155 offset1:1
	ds_read2_b32 v[188:189], v155 offset0:2 offset1:3
	v_mad_u64_u32 v[190:191], s[18:19], s38, v180, 0
	v_lshl_add_u64 v[190:191], v[190:191], 1, s[14:15]
	v_lshl_add_u64 v[190:191], v[190:191], 0, v[166:167]
	s_waitcnt lgkmcnt(0)
	global_store_dwordx4 v[190:191], v[186:189], off sc0 sc1
	s_branch .LBB0_1539

.LBB0_1846:
	s_waitcnt vmcnt(1)
	v_mul_f32_e32 v153, v32, v186
	s_waitcnt vmcnt(0)
	v_mul_f32_e32 v155, v60, v187
	v_cvt_pk_bf16_f32 v153, v153, v155
	ds_write_b32 v145, v153 offset:112
	v_mul_f32_e32 v153, v33, v186
	v_mul_f32_e32 v155, v61, v187
	v_cvt_pk_bf16_f32 v153, v153, v155
	ds_write_b32 v145, v153 offset:244
	v_mul_f32_e32 v153, v34, v186
	v_mul_f32_e32 v155, v62, v187
	v_cvt_pk_bf16_f32 v153, v153, v155
	ds_write_b32 v145, v153 offset:376
	v_mul_f32_e32 v153, v35, v186
	v_mul_f32_e32 v155, v63, v187
	v_cvt_pk_bf16_f32 v153, v153, v155
	ds_write_b32 v145, v153 offset:508
	ds_read2_b32 v[186:187], v147 offset1:1
	ds_read2_b32 v[188:189], v147 offset0:2 offset1:3
	v_mad_u64_u32 v[190:191], s[6:7], s35, v130, 0
	v_lshl_add_u64 v[190:191], v[190:191], 1, s[10:11]
	ds_read2_b32 v[194:195], v149 offset1:1
	ds_read2_b32 v[196:197], v149 offset0:2 offset1:3
	v_lshl_add_u64 v[190:191], v[190:191], 0, v[166:167]
	s_waitcnt lgkmcnt(2)
	global_store_dwordx4 v[190:191], v[186:189], off sc0 sc1
	v_cmp_gt_i32_e32 vcc, s37, v170
	s_nop 0
	v_mad_u64_u32 v[186:187], s[6:7], s35, v168, 0
	v_lshl_add_u64 v[186:187], v[186:187], 1, s[10:11]
	v_lshl_add_u64 v[186:187], v[186:187], 0, v[166:167]
	s_waitcnt lgkmcnt(0)
	global_store_dwordx4 v[186:187], v[194:197], off sc0 sc1
	s_and_saveexec_b64 s[6:7], vcc
	s_cbranch_execz .LBB0_1853
	v_add_u32_e32 v153, v129, v131
	ds_read2_b32 v[186:187], v153 offset1:1
	ds_read2_b32 v[188:189], v153 offset0:2 offset1:3
	v_mad_u64_u32 v[190:191], s[18:19], s35, v170, 0
	v_lshl_add_u64 v[190:191], v[190:191], 1, s[10:11]
	v_lshl_add_u64 v[190:191], v[190:191], 0, v[166:167]
	s_waitcnt lgkmcnt(0)
	global_store_dwordx4 v[190:191], v[186:189], off sc0 sc1
	s_or_b64 exec, exec, s[6:7]
	v_cmp_gt_i32_e32 vcc, s37, v172
	s_and_saveexec_b64 s[6:7], vcc
	s_cbranch_execnz .LBB0_1854

.LBB0_1849:
	v_add_u32_e32 v153, v129, v137
	ds_read2_b32 v[186:187], v153 offset1:1
	ds_read2_b32 v[188:189], v153 offset0:2 offset1:3
	v_mad_u64_u32 v[190:191], s[18:19], s35, v174, 0
	v_lshl_add_u64 v[190:191], v[190:191], 1, s[10:11]
	v_lshl_add_u64 v[190:191], v[190:191], 0, v[166:167]
	s_waitcnt lgkmcnt(0)
	global_store_dwordx4 v[190:191], v[186:189], off sc0 sc1
	s_or_b64 exec, exec, s[6:7]
	v_cmp_gt_i32_e32 vcc, s37, v176
	s_and_saveexec_b64 s[6:7], vcc
	s_cbranch_execnz .LBB0_1856

.LBB0_1851:
	v_add_u32_e32 v153, v129, v141
	ds_read2_b32 v[186:187], v153 offset1:1
	ds_read2_b32 v[188:189], v153 offset0:2 offset1:3
	v_mad_u64_u32 v[190:191], s[18:19], s35, v178, 0
	v_lshl_add_u64 v[190:191], v[190:191], 1, s[10:11]
	v_lshl_add_u64 v[190:191], v[190:191], 0, v[166:167]
	s_waitcnt lgkmcnt(0)
	global_store_dwordx4 v[190:191], v[186:189], off sc0 sc1
	s_or_b64 exec, exec, s[6:7]
	v_cmp_gt_i32_e32 vcc, s37, v180
	s_and_saveexec_b64 s[6:7], vcc
	s_cbranch_execnz .LBB0_1858

.LBB0_1854:
	v_add_u32_e32 v153, v129, v135
	ds_read2_b32 v[186:187], v153 offset1:1
	ds_read2_b32 v[188:189], v153 offset0:2 offset1:3
	v_mad_u64_u32 v[190:191], s[18:19], s35, v172, 0
	v_lshl_add_u64 v[190:191], v[190:191], 1, s[10:11]
	v_lshl_add_u64 v[190:191], v[190:191], 0, v[166:167]
	s_waitcnt lgkmcnt(0)
	global_store_dwordx4 v[190:191], v[186:189], off sc0 sc1
	s_or_b64 exec, exec, s[6:7]
	v_cmp_gt_i32_e32 vcc, s37, v174
	s_and_saveexec_b64 s[6:7], vcc
	s_cbranch_execnz .LBB0_1849

.LBB0_1856:
	v_add_u32_e32 v153, v129, v139
	ds_read2_b32 v[186:187], v153 offset1:1
	ds_read2_b32 v[188:189], v153 offset0:2 offset1:3
	v_mad_u64_u32 v[190:191], s[18:19], s35, v176, 0
	v_lshl_add_u64 v[190:191], v[190:191], 1, s[10:11]
	v_lshl_add_u64 v[190:191], v[190:191], 0, v[166:167]
	s_waitcnt lgkmcnt(0)
	global_store_dwordx4 v[190:191], v[186:189], off sc0 sc1
	s_or_b64 exec, exec, s[6:7]
	v_cmp_gt_i32_e32 vcc, s37, v178
	s_and_saveexec_b64 s[6:7], vcc
	s_cbranch_execnz .LBB0_1851

.LBB0_1858:
	v_add_u32_e32 v153, v129, v143
	ds_read2_b32 v[186:187], v153 offset1:1
	ds_read2_b32 v[188:189], v153 offset0:2 offset1:3
	v_mad_u64_u32 v[190:191], s[18:19], s35, v180, 0
	v_lshl_add_u64 v[190:191], v[190:191], 1, s[10:11]
	v_lshl_add_u64 v[190:191], v[190:191], 0, v[166:167]
	s_waitcnt lgkmcnt(0)
	global_store_dwordx4 v[190:191], v[186:189], off sc0 sc1
	s_or_b64 exec, exec, s[6:7]
	s_andn2_b64 vcc, exec, s[16:17]
	s_mov_b64 s[16:17], 0
	s_cbranch_vccnz .LBB0_1783

.LBB0_1922:
	s_nop 0
	v_mul_f32_e32 v151, v120, v186
	v_mul_f32_e32 v153, v124, v187
	v_cvt_pk_bf16_f32 v151, v151, v153
	ds_write_b32 v145, v151 offset:112
	v_mul_f32_e32 v151, v121, v186
	v_mul_f32_e32 v153, v125, v187
	v_cvt_pk_bf16_f32 v151, v151, v153
	ds_write_b32 v145, v151 offset:244
	v_mul_f32_e32 v151, v122, v186
	v_mul_f32_e32 v153, v126, v187
	v_cvt_pk_bf16_f32 v151, v151, v153
	ds_write_b32 v145, v151 offset:376
	v_mul_f32_e32 v151, v123, v186
	v_mul_f32_e32 v153, v127, v187
	v_cvt_pk_bf16_f32 v151, v151, v153
	ds_write_b32 v145, v151 offset:508
	ds_read2_b32 v[186:187], v147 offset1:1
	ds_read2_b32 v[188:189], v147 offset0:2 offset1:3
	v_mad_u64_u32 v[190:191], s[6:7], s34, v130, 0
	v_lshl_add_u64 v[190:191], v[190:191], 1, s[14:15]
	ds_read2_b32 v[194:195], v149 offset1:1
	ds_read2_b32 v[196:197], v149 offset0:2 offset1:3
	v_lshl_add_u64 v[190:191], v[190:191], 0, v[166:167]
	s_waitcnt lgkmcnt(2)
	global_store_dwordx4 v[190:191], v[186:189], off sc0 sc1
	v_cmp_gt_i32_e32 vcc, s39, v170
	s_nop 0
	v_mad_u64_u32 v[186:187], s[6:7], s34, v168, 0
	v_lshl_add_u64 v[186:187], v[186:187], 1, s[14:15]
	v_lshl_add_u64 v[186:187], v[186:187], 0, v[166:167]
	s_waitcnt lgkmcnt(0)
	global_store_dwordx4 v[186:187], v[194:197], off sc0 sc1
	s_and_saveexec_b64 s[6:7], vcc
	s_cbranch_execz .LBB0_1928
	v_add_u32_e32 v151, v129, v131
	ds_read2_b32 v[186:187], v151 offset1:1
	ds_read2_b32 v[188:189], v151 offset0:2 offset1:3
	v_mad_u64_u32 v[190:191], s[18:19], s34, v170, 0
	v_lshl_add_u64 v[190:191], v[190:191], 1, s[14:15]
	v_lshl_add_u64 v[190:191], v[190:191], 0, v[166:167]
	s_waitcnt lgkmcnt(0)
	global_store_dwordx4 v[190:191], v[186:189], off sc0 sc1
	s_or_b64 exec, exec, s[6:7]
	v_cmp_gt_i32_e32 vcc, s39, v172
	s_and_saveexec_b64 s[6:7], vcc
	s_cbranch_execnz .LBB0_1929

.LBB0_1925:
	v_add_u32_e32 v151, v129, v137
	ds_read2_b32 v[186:187], v151 offset1:1
	ds_read2_b32 v[188:189], v151 offset0:2 offset1:3
	v_mad_u64_u32 v[190:191], s[18:19], s34, v174, 0
	v_lshl_add_u64 v[190:191], v[190:191], 1, s[14:15]
	v_lshl_add_u64 v[190:191], v[190:191], 0, v[166:167]
	s_waitcnt lgkmcnt(0)
	global_store_dwordx4 v[190:191], v[186:189], off sc0 sc1
	s_or_b64 exec, exec, s[6:7]
	v_cmp_gt_i32_e32 vcc, s39, v176
	s_and_saveexec_b64 s[6:7], vcc
	s_cbranch_execnz .LBB0_1931

.LBB0_1927:
	v_add_u32_e32 v151, v129, v141
	ds_read2_b32 v[186:187], v151 offset1:1
	ds_read2_b32 v[188:189], v151 offset0:2 offset1:3
	v_mad_u64_u32 v[190:191], s[18:19], s34, v178, 0
	v_lshl_add_u64 v[190:191], v[190:191], 1, s[14:15]
	v_lshl_add_u64 v[190:191], v[190:191], 0, v[166:167]
	s_waitcnt lgkmcnt(0)
	global_store_dwordx4 v[190:191], v[186:189], off sc0 sc1
	s_or_b64 exec, exec, s[6:7]
	v_cmp_gt_i32_e32 vcc, s39, v180
	s_and_saveexec_b64 s[6:7], vcc
	s_cbranch_execz .LBB0_1782
	s_branch .LBB0_1933

.LBB0_1929:
	v_add_u32_e32 v151, v129, v135
	ds_read2_b32 v[186:187], v151 offset1:1
	ds_read2_b32 v[188:189], v151 offset0:2 offset1:3
	v_mad_u64_u32 v[190:191], s[18:19], s34, v172, 0
	v_lshl_add_u64 v[190:191], v[190:191], 1, s[14:15]
	v_lshl_add_u64 v[190:191], v[190:191], 0, v[166:167]
	s_waitcnt lgkmcnt(0)
	global_store_dwordx4 v[190:191], v[186:189], off sc0 sc1
	s_or_b64 exec, exec, s[6:7]
	v_cmp_gt_i32_e32 vcc, s39, v174
	s_and_saveexec_b64 s[6:7], vcc
	s_cbranch_execnz .LBB0_1925

.LBB0_1931:
	v_add_u32_e32 v151, v129, v139
	ds_read2_b32 v[186:187], v151 offset1:1
	ds_read2_b32 v[188:189], v151 offset0:2 offset1:3
	v_mad_u64_u32 v[190:191], s[18:19], s34, v176, 0
	v_lshl_add_u64 v[190:191], v[190:191], 1, s[14:15]
	v_lshl_add_u64 v[190:191], v[190:191], 0, v[166:167]
	s_waitcnt lgkmcnt(0)
	global_store_dwordx4 v[190:191], v[186:189], off sc0 sc1
	s_or_b64 exec, exec, s[6:7]
	v_cmp_gt_i32_e32 vcc, s39, v178
	s_and_saveexec_b64 s[6:7], vcc
	s_cbranch_execnz .LBB0_1927

.LBB0_1933:
	v_add_u32_e32 v151, v129, v143
	ds_read2_b32 v[186:187], v151 offset1:1
	ds_read2_b32 v[188:189], v151 offset0:2 offset1:3
	v_mad_u64_u32 v[190:191], s[18:19], s34, v180, 0
	v_lshl_add_u64 v[190:191], v[190:191], 1, s[14:15]
	v_lshl_add_u64 v[190:191], v[190:191], 0, v[166:167]
	s_waitcnt lgkmcnt(0)
	global_store_dwordx4 v[190:191], v[186:189], off sc0 sc1
	s_branch .LBB0_1782
